# bubble weight-prep tile loops: 4 tile loads issued together into extra VGPRs with counted waits instead of 3 serial load-wait round trips
# speedup vs baseline: 1.0143x; 1.0069x over previous
.LBB0_205:
	s_or_saveexec_b64 s[4:5], s[4:5]
	v_mov_b32_e32 v2, 0
	v_mov_b32_e32 v3, 0
	v_mov_b32_e32 v4, 0
	v_mov_b32_e32 v5, 0
	v_mov_b32_e32 v6, 0
	v_mov_b32_e32 v7, 0
	v_mov_b32_e32 v8, 0
	v_mov_b32_e32 v9, 0
	s_xor_b64 exec, exec, s[4:5]
	s_cbranch_execz .LBB0_207
	s_mul_i32 s12, s10, 0xffa80000
	v_ashrrev_i32_e32 v11, 31, v10
	v_add_u32_e32 v8, s12, v16
	v_lshl_add_u64 v[6:7], v[10:11], 2, s[0:1]
	v_ashrrev_i32_e32 v9, 31, v8
	v_add_u32_e32 v4, 0x16000, v8
	v_lshl_add_u64 v[2:3], v[8:9], 2, v[6:7]
	v_ashrrev_i32_e32 v5, 31, v4
	v_lshl_add_u64 v[10:11], v[4:5], 2, v[6:7]
	global_load_dwordx4 v[140:143], v[2:3], off
	global_load_dwordx4 v[144:147], v[10:11], off
	v_add_u32_e32 v2, 0x2c000, v8
	v_add_u32_e32 v8, 0x42000, v8
	v_ashrrev_i32_e32 v3, 31, v2
	v_ashrrev_i32_e32 v9, 31, v8
	v_lshl_add_u64 v[2:3], v[2:3], 2, v[6:7]
	v_lshl_add_u64 v[6:7], v[8:9], 2, v[6:7]
	global_load_dwordx4 v[2:5], v[2:3], off
	s_nop 0
	global_load_dwordx4 v[6:9], v[6:7], off
	s_waitcnt vmcnt(3)
	ds_write2_b32 v17, v140, v141 offset1:1
	ds_write2_b32 v17, v142, v143 offset0:2 offset1:3
	s_waitcnt vmcnt(2)
	ds_write2_b32 v18, v144, v145 offset1:1
	ds_write2_b32 v19, v146, v147 offset1:1

.LBB0_214:
	s_or_saveexec_b64 s[4:5], s[4:5]
	s_mulk_i32 s8, 0xf500
	v_mov_b32_e32 v2, 0
	v_mov_b32_e32 v3, 0
	v_mov_b32_e32 v4, 0
	v_mov_b32_e32 v5, 0
	v_mov_b32_e32 v6, 0
	v_mov_b32_e32 v7, 0
	v_mov_b32_e32 v8, 0
	v_mov_b32_e32 v9, 0
	s_xor_b64 exec, exec, s[4:5]
	s_cbranch_execz .LBB0_216
	s_add_i32 s9, s8, s6
	v_add_u32_e32 v8, s9, v12
	v_ashrrev_i32_e32 v11, 31, v10
	v_ashrrev_i32_e32 v9, 31, v8
	v_add_u32_e32 v4, 16, v8
	v_lshl_add_u64 v[6:7], v[10:11], 2, s[0:1]
	v_lshlrev_b64 v[2:3], 12, v[8:9]
	v_ashrrev_i32_e32 v5, 31, v4
	v_lshl_add_u64 v[2:3], v[6:7], 0, v[2:3]
	v_lshlrev_b64 v[4:5], 12, v[4:5]
	v_lshl_add_u64 v[10:11], v[6:7], 0, v[4:5]
	global_load_dwordx4 v[140:143], v[2:3], off
	global_load_dwordx4 v[144:147], v[10:11], off
	v_add_u32_e32 v2, 32, v8
	v_add_u32_e32 v8, 48, v8
	v_ashrrev_i32_e32 v3, 31, v2
	v_ashrrev_i32_e32 v9, 31, v8
	v_lshlrev_b64 v[2:3], 12, v[2:3]
	v_lshlrev_b64 v[8:9], 12, v[8:9]
	v_lshl_add_u64 v[2:3], v[6:7], 0, v[2:3]
	v_lshl_add_u64 v[6:7], v[6:7], 0, v[8:9]
	global_load_dwordx4 v[2:5], v[2:3], off
	s_nop 0
	global_load_dwordx4 v[6:9], v[6:7], off
	s_waitcnt vmcnt(3)
	ds_write2_b32 v17, v140, v141 offset1:1
	ds_write2_b32 v17, v142, v143 offset0:2 offset1:3
	s_waitcnt vmcnt(2)
	ds_write2_b32 v18, v144, v145 offset1:1
	ds_write2_b32 v19, v146, v147 offset1:1

.LBB0_1494:
	s_or_saveexec_b64 s[4:5], s[4:5]
	v_mov_b32_e32 v2, 0
	v_mov_b32_e32 v3, 0
	v_mov_b32_e32 v4, 0
	v_mov_b32_e32 v5, 0
	v_mov_b32_e32 v6, 0
	v_mov_b32_e32 v7, 0
	v_mov_b32_e32 v8, 0
	v_mov_b32_e32 v9, 0
	s_xor_b64 exec, exec, s[4:5]
	s_cbranch_execz .LBB0_1496
	v_readlane_b32 s12, v253, 9
	v_ashrrev_i32_e32 v11, 31, v10
	v_readlane_b32 s13, v253, 10
	s_nop 1
	v_lshl_add_u64 v[6:7], v[10:11], 2, s[12:13]
	s_mul_i32 s12, s10, 0xffa80000
	v_add_u32_e32 v8, s12, v16
	v_ashrrev_i32_e32 v9, 31, v8
	v_add_u32_e32 v4, 0x16000, v8
	v_lshl_add_u64 v[2:3], v[8:9], 2, v[6:7]
	v_ashrrev_i32_e32 v5, 31, v4
	v_lshl_add_u64 v[10:11], v[4:5], 2, v[6:7]
	global_load_dwordx4 v[140:143], v[2:3], off
	global_load_dwordx4 v[144:147], v[10:11], off
	v_add_u32_e32 v2, 0x2c000, v8
	v_add_u32_e32 v8, 0x42000, v8
	v_ashrrev_i32_e32 v3, 31, v2
	v_ashrrev_i32_e32 v9, 31, v8
	v_lshl_add_u64 v[2:3], v[2:3], 2, v[6:7]
	v_lshl_add_u64 v[6:7], v[8:9], 2, v[6:7]
	global_load_dwordx4 v[2:5], v[2:3], off
	s_nop 0
	global_load_dwordx4 v[6:9], v[6:7], off
	s_waitcnt vmcnt(3)
	ds_write2_b32 v17, v140, v141 offset1:1
	ds_write2_b32 v17, v142, v143 offset0:2 offset1:3
	s_waitcnt vmcnt(2)
	ds_write2_b32 v18, v144, v145 offset1:1
	ds_write2_b32 v19, v146, v147 offset1:1

.LBB0_1503:
	s_or_saveexec_b64 s[4:5], s[4:5]
	s_mulk_i32 s8, 0xf500
	v_mov_b32_e32 v2, 0
	v_mov_b32_e32 v3, 0
	v_mov_b32_e32 v4, 0
	v_mov_b32_e32 v5, 0
	v_mov_b32_e32 v6, 0
	v_mov_b32_e32 v7, 0
	v_mov_b32_e32 v8, 0
	v_mov_b32_e32 v9, 0
	s_xor_b64 exec, exec, s[4:5]
	s_cbranch_execz .LBB0_1505
	s_add_i32 s9, s8, s6
	v_readlane_b32 s10, v253, 11
	v_add_u32_e32 v8, s9, v12
	v_ashrrev_i32_e32 v11, 31, v10
	v_readlane_b32 s11, v253, 12
	v_ashrrev_i32_e32 v9, 31, v8
	v_add_u32_e32 v4, 16, v8
	v_lshl_add_u64 v[6:7], v[10:11], 2, s[10:11]
	v_lshlrev_b64 v[2:3], 12, v[8:9]
	v_ashrrev_i32_e32 v5, 31, v4
	v_lshl_add_u64 v[2:3], v[6:7], 0, v[2:3]
	v_lshlrev_b64 v[4:5], 12, v[4:5]
	v_lshl_add_u64 v[10:11], v[6:7], 0, v[4:5]
	global_load_dwordx4 v[140:143], v[2:3], off
	global_load_dwordx4 v[144:147], v[10:11], off
	v_add_u32_e32 v2, 32, v8
	v_add_u32_e32 v8, 48, v8
	v_ashrrev_i32_e32 v3, 31, v2
	v_ashrrev_i32_e32 v9, 31, v8
	v_lshlrev_b64 v[2:3], 12, v[2:3]
	v_lshlrev_b64 v[8:9], 12, v[8:9]
	v_lshl_add_u64 v[2:3], v[6:7], 0, v[2:3]
	v_lshl_add_u64 v[6:7], v[6:7], 0, v[8:9]
	global_load_dwordx4 v[2:5], v[2:3], off
	s_nop 0
	global_load_dwordx4 v[6:9], v[6:7], off
	s_waitcnt vmcnt(3)
	ds_write2_b32 v17, v140, v141 offset1:1
	ds_write2_b32 v17, v142, v143 offset0:2 offset1:3
	s_waitcnt vmcnt(2)
	ds_write2_b32 v18, v144, v145 offset1:1
	ds_write2_b32 v19, v146, v147 offset1:1
